# phase-10 K loop: same first-iteration wait relaxation as phase 1 (epilogue issues 8 statistic loads + 8 stores: vmcnt 24 in the first K iteration of a tile, counted wait before the phase-7 fragment re
# baseline (speedup 1.0000x reference)
.LBB0_1089:
	s_lshl_b32 s5, s6, 5
	s_mov_b64 s[6:7], 0x80
	s_and_b32 s10, s5, 0x60
	s_add_i32 m0, s47, 0x18000
	v_lshl_add_u64 v[6:7], v[6:7], 0, s[6:7]
	s_ashr_i32 s52, s90, 31
	s_lshl_b32 s8, s3, 13
	s_lshl_b32 s28, s10, 7
	s_waitcnt vmcnt(4)
	s_barrier
	global_load_lds_dwordx4 v[6:7], off
	v_lshl_add_u64 v[4:5], v[4:5], 0, s[6:7]
	s_add_i32 m0, s47, 0x1a000
	s_add_i32 s53, s47, 0x8000
	s_add_i32 s54, s47, 0xa000
	global_load_lds_dwordx4 v[4:5], off
	v_lshl_add_u64 v[2:3], v[2:3], 0, s[6:7]
	s_mov_b32 m0, s53
	s_add_u32 s12, s42, 0x40080
	global_load_lds_dwordx4 v[2:3], off
	v_lshl_add_u64 v[0:1], v[0:1], 0, s[6:7]
	s_mov_b32 m0, s54
	s_addc_u32 s13, s43, 0
	global_load_lds_dwordx4 v[0:1], off
	s_add_i32 m0, s47, 0x1c000
	v_lshl_add_u64 v[0:1], s[12:13], 0, v[132:133]
	global_load_lds_dwordx4 v[0:1], off
	v_lshl_add_u64 v[0:1], s[12:13], 0, v[128:129]
	s_add_i32 m0, s47, 0x1e000
	v_bfe_u32 v2, v9, 4, 2
	global_load_lds_dwordx4 v[0:1], off
	v_and_b32_e32 v1, 15, v9
	v_lshlrev_b32_e32 v0, 4, v2
	v_lshlrev_b32_e32 v3, 2, v9
	v_lshl_or_b32 v155, s3, 6, v1
	v_lshl_or_b32 v1, v1, 6, v0
	v_and_b32_e32 v3, 32, v3
	v_bitop3_b32 v4, v1, s8, v3 bitop3:0xde
	v_bitop3_b32 v159, v1, s28, v3 bitop3:0xde
	v_mov_b32_e32 v1, v133
	v_lshl_add_u64 v[136:137], s[0:1], 0, v[0:1]
	v_lshlrev_b32_e32 v0, 14, v13
	v_and_b32_e32 v0, 0xffff8000, v0
	v_lshl_add_u32 v0, v12, 11, v0
	v_and_b32_e32 v1, 1, v13
	v_lshl_or_b32 v0, v1, 6, v0
	v_lshl_add_u32 v138, v14, 1, v0
	v_lshlrev_b32_e32 v0, 14, v8
	v_and_b32_e32 v0, 0xffff8000, v0
	v_lshl_add_u32 v0, v10, 11, v0
	v_and_b32_e32 v1, 1, v8
	s_waitcnt vmcnt(6)
	v_lshl_or_b32 v0, v1, 6, v0
	v_lshl_add_u32 v140, v11, 1, v0
	s_add_i32 s56, 0, 0x10000
	s_add_i32 s57, 0, 0x14000
	v_mbcnt_lo_u32_b32 v0, -1, 0
	s_sext_i32_i8 s5, s2
	s_mov_b32 s55, s90
	v_lshl_or_b32 v163, v2, 3, s10
	v_mov_b32_e32 v139, v133
	v_mov_b32_e32 v141, v133
	v_mov_b64_e32 v[142:143], 0xb00
	v_mov_b64_e32 v[144:145], 0xaff
	v_add_u32_e32 v167, s56, v159
	v_add_u32_e32 v171, 0, v4
	v_add_u32_e32 v175, s57, v159
	v_mbcnt_hi_u32_b32 v177, -1, v0
	s_mov_b32 s8, 0x3a800000
	s_mov_b32 s10, 0x358637bd
	s_mov_b32 s58, 0x800000
	s_movk_i32 s59, 0x1600
	s_mov_b32 s96, s4
	s_mov_b32 s97, s5
	v_lshl_add_u32 v168, s4, 8, v155
	v_ashrrev_i32_e32 v169, 31, v168
	v_or_b32_e32 v164, 16, v168
	v_lshlrev_b64 v[146:147], 6, v[168:169]
	v_ashrrev_i32_e32 v165, 31, v164
	v_or_b32_e32 v160, 32, v168
	v_lshl_add_u64 v[146:147], v[136:137], 0, v[146:147]
	v_lshlrev_b64 v[148:149], 6, v[164:165]
	v_ashrrev_i32_e32 v161, 31, v160
	v_lshl_add_u64 v[148:149], v[136:137], 0, v[148:149]
	global_load_dwordx4 v[178:181], v[146:147], off
	global_load_dwordx4 v[182:185], v[148:149], off
	v_lshlrev_b64 v[146:147], 6, v[160:161]
	v_or_b32_e32 v156, 48, v168
	v_lshl_add_u64 v[146:147], v[136:137], 0, v[146:147]
	v_ashrrev_i32_e32 v157, 31, v156
	global_load_dwordx4 v[186:189], v[146:147], off
	v_lshlrev_b64 v[146:147], 6, v[156:157]
	v_lshl_add_u64 v[146:147], v[136:137], 0, v[146:147]
	global_load_dwordx4 v[196:199], v[146:147], off
	v_add_u32_e32 v152, 0x80, v168
	v_ashrrev_i32_e32 v153, 31, v152
	v_lshlrev_b64 v[146:147], 6, v[152:153]
	v_add_u32_e32 v150, 0x90, v168
	v_lshl_add_u64 v[146:147], v[136:137], 0, v[146:147]
	v_ashrrev_i32_e32 v151, 31, v150
	global_load_dwordx4 v[200:203], v[146:147], off
	v_lshlrev_b64 v[146:147], 6, v[150:151]
	v_lshl_add_u64 v[146:147], v[136:137], 0, v[146:147]
	global_load_dwordx4 v[204:207], v[146:147], off
	v_and_b32_e32 v147, 64, v177
	v_add_u32_e32 v148, 0xa0, v168
	v_add_u32_e32 v146, 0xb0, v168
	v_add_u32_e32 v154, 64, v147
	v_ashrrev_i32_e32 v149, 31, v148
	v_ashrrev_i32_e32 v147, 31, v146
	v_lshlrev_b64 v[208:209], 6, v[148:149]
	v_lshlrev_b64 v[210:211], 6, v[146:147]
	v_lshl_add_u64 v[208:209], v[136:137], 0, v[208:209]
	v_lshl_add_u64 v[212:213], v[136:137], 0, v[210:211]
	global_load_dwordx4 v[208:211], v[208:209], off
	s_nop 0
	global_load_dwordx4 v[212:215], v[212:213], off
	v_xor_b32_e32 v151, 16, v177
	v_cmp_lt_i32_e32 vcc, v151, v154
	v_xor_b32_e32 v153, 32, v177
	v_mov_b64_e32 v[190:191], s[10:11]
	v_cndmask_b32_e32 v151, v177, v151, vcc
	v_lshlrev_b32_e32 v147, 2, v151
	v_cmp_lt_i32_e32 vcc, v153, v154
	v_lshl_or_b32 v172, s5, 7, v163
	s_waitcnt vmcnt(0)
	v_mov_b32_e32 v216, v179
	v_mov_b32_e32 v217, v180
	v_mov_b32_e32 v179, v181
	v_mov_b32_e32 v180, v183
	v_mov_b32_e32 v181, v184
	v_mov_b32_e32 v183, v185
	v_pk_add_f32 v[178:179], v[216:217], v[178:179]
	v_pk_add_f32 v[180:181], v[180:181], v[182:183]
	v_mov_b32_e32 v183, v178
	v_mov_b32_e32 v182, v180
	v_mov_b32_e32 v178, v181
	v_mov_b32_e32 v184, v187
	v_mov_b32_e32 v185, v188
	v_mov_b32_e32 v187, v189
	v_mov_b32_e32 v188, v197
	v_mov_b32_e32 v189, v198
	v_mov_b32_e32 v197, v199
	v_pk_add_f32 v[178:179], v[182:183], v[178:179]
	v_pk_add_f32 v[184:185], v[184:185], v[186:187]
	v_pk_add_f32 v[186:187], v[188:189], v[196:197]
	ds_bpermute_b32 v183, v147, v179
	ds_bpermute_b32 v182, v147, v178
	v_mov_b32_e32 v180, v186
	v_mov_b32_e32 v181, v184
	v_mov_b32_e32 v184, v187
	v_pk_add_f32 v[180:181], v[180:181], v[184:185]
	ds_bpermute_b32 v185, v147, v181
	ds_bpermute_b32 v184, v147, v180
	v_cndmask_b32_e32 v153, v177, v153, vcc
	v_lshlrev_b32_e32 v149, 2, v153
	s_waitcnt lgkmcnt(0)
	v_pk_add_f32 v[178:179], v[178:179], v[182:183]
	ds_bpermute_b32 v183, v149, v179
	ds_bpermute_b32 v182, v149, v178
	v_pk_add_f32 v[180:181], v[180:181], v[184:185]
	ds_bpermute_b32 v185, v149, v181
	ds_bpermute_b32 v184, v149, v180
	v_mov_b32_e32 v186, v201
	s_waitcnt lgkmcnt(2)
	v_pk_add_f32 v[178:179], v[178:179], v[182:183]
	v_mov_b32_e32 v187, v202
	v_mov_b32_e32 v201, v203
	v_mov_b32_e32 v188, v205
	v_pk_fma_f32 v[178:179], v[178:179], s[8:9], v[190:191] op_sel_hi:[1,0,0]
	v_mov_b32_e32 v189, v206
	v_mov_b32_e32 v205, v207
	v_pk_add_f32 v[186:187], v[186:187], v[200:201]
	v_mul_f32_e32 v151, 0x4b800000, v179
	v_cmp_gt_f32_e32 vcc, s58, v179
	v_pk_add_f32 v[182:183], v[188:189], v[204:205]
	s_waitcnt lgkmcnt(0)
	v_pk_add_f32 v[180:181], v[180:181], v[184:185]
	v_cndmask_b32_e32 v151, v179, v151, vcc
	v_mov_b32_e32 v184, v182
	v_mov_b32_e32 v185, v186
	v_mov_b32_e32 v186, v183
	v_rsq_f32_e32 v151, v151
	v_pk_add_f32 v[182:183], v[184:185], v[186:187]
	ds_bpermute_b32 v185, v147, v183
	ds_bpermute_b32 v184, v147, v182
	v_pk_fma_f32 v[180:181], v[180:181], s[8:9], v[190:191] op_sel_hi:[1,0,0]
	v_mul_f32_e32 v153, 0x4b800000, v178
	v_cmp_gt_f32_e64 s[0:1], s58, v178
	v_mul_f32_e32 v157, 0x45800000, v151
	v_mul_f32_e32 v154, 0x4b800000, v181
	v_cndmask_b32_e64 v153, v178, v153, s[0:1]
	v_cmp_gt_f32_e64 s[4:5], s58, v181
	v_cndmask_b32_e32 v178, v151, v157, vcc
	v_mul_f32_e32 v151, 0x4b800000, v180
	v_cmp_gt_f32_e32 vcc, s58, v180
	v_cndmask_b32_e64 v154, v181, v154, s[4:5]
	v_rsq_f32_e32 v153, v153
	v_cndmask_b32_e32 v151, v180, v151, vcc
	s_waitcnt lgkmcnt(0)
	v_pk_add_f32 v[180:181], v[182:183], v[184:185]
	ds_bpermute_b32 v183, v149, v181
	ds_bpermute_b32 v182, v149, v180
	v_mov_b32_e32 v184, v213
	v_mov_b32_e32 v185, v214
	v_mov_b32_e32 v213, v215
	v_pk_add_f32 v[184:185], v[184:185], v[212:213]
	s_waitcnt lgkmcnt(0)
	v_pk_add_f32 v[180:181], v[180:181], v[182:183]
	v_mov_b32_e32 v182, v209
	v_mov_b32_e32 v183, v210
	v_mov_b32_e32 v209, v211
	v_pk_add_f32 v[182:183], v[182:183], v[208:209]
	v_mov_b32_e32 v186, v184
	v_mov_b32_e32 v187, v182
	v_mov_b32_e32 v182, v185
	v_rsq_f32_e32 v154, v154
	v_pk_add_f32 v[182:183], v[186:187], v[182:183]
	ds_bpermute_b32 v185, v147, v183
	ds_bpermute_b32 v184, v147, v182
	v_mul_f32_e32 v158, 0x45800000, v153
	v_cndmask_b32_e64 v176, v153, v158, s[0:1]
	v_mul_f32_e32 v153, 0x45800000, v154
	v_pk_fma_f32 v[180:181], v[180:181], s[8:9], v[190:191] op_sel_hi:[1,0,0]
	v_cndmask_b32_e64 v174, v154, v153, s[4:5]
	v_mul_f32_e32 v154, 0x4b800000, v181
	v_cmp_gt_f32_e64 s[0:1], s58, v181
	v_mul_f32_e32 v147, 0x4b800000, v180
	v_cmp_gt_f32_e64 s[4:5], s58, v180
	v_cndmask_b32_e64 v154, v181, v154, s[0:1]
	v_rsq_f32_e32 v151, v151
	v_cndmask_b32_e64 v147, v180, v147, s[4:5]
	s_waitcnt lgkmcnt(0)
	v_pk_add_f32 v[180:181], v[182:183], v[184:185]
	ds_bpermute_b32 v183, v149, v181
	ds_bpermute_b32 v182, v149, v180
	v_rsq_f32_e32 v154, v154
	v_mul_f32_e32 v153, 0x45800000, v151
	v_cndmask_b32_e32 v170, v151, v153, vcc
	v_rsq_f32_e32 v147, v147
	s_waitcnt lgkmcnt(0)
	v_pk_add_f32 v[180:181], v[180:181], v[182:183]
	v_mul_f32_e32 v149, 0x45800000, v154
	v_pk_fma_f32 v[180:181], v[180:181], s[8:9], v[190:191] op_sel_hi:[1,0,0]
	v_cndmask_b32_e64 v166, v154, v149, s[0:1]
	v_mul_f32_e32 v151, 0x4b800000, v181
	v_cmp_gt_f32_e32 vcc, s58, v181
	v_mul_f32_e32 v153, 0x4b800000, v180
	v_cmp_gt_f32_e64 s[0:1], s58, v180
	v_cndmask_b32_e32 v151, v181, v151, vcc
	v_rsq_f32_e32 v151, v151
	v_cndmask_b32_e64 v153, v180, v153, s[0:1]
	v_rsq_f32_e32 v153, v153
	v_mul_f32_e32 v149, 0x45800000, v147
	v_cndmask_b32_e64 v162, v147, v149, s[4:5]
	v_mul_f32_e32 v147, 0x45800000, v151
	v_cndmask_b32_e32 v158, v151, v147, vcc
	v_mul_f32_e32 v147, 0x45800000, v153
	v_cndmask_b32_e64 v154, v153, v147, s[0:1]
	v_mov_b32_e32 v240, v178
	v_mov_b32_e32 v241, v154
	s_mov_b32 s4, s96
	s_mov_b32 s5, s97
	s_barrier
	s_mov_b32 s98, 0

.LBB0_1093:
	ds_read_b128 v[146:149], v167
	ds_read_b128 v[150:153], v167 offset:1024
	ds_read_b128 v[178:181], v167 offset:2048
	ds_read_b128 v[182:185], v167 offset:3072
	s_add_u32 s28, s0, 0xfffc0080
	s_addc_u32 s29, s1, -1
	s_cmp_eq_u32 s64, 12
	s_cselect_b32 s45, s37, s29
	s_cselect_b32 s44, s60, s28
	s_cselect_b32 s43, s13, s63
	s_cselect_b32 s42, s61, s62
	v_lshl_add_u64 v[156:157], s[0:1], 0, v[138:139]
	s_add_i32 m0, s47, 0xc000
	ds_read_b128 v[186:189], v171
	ds_read_b128 v[196:199], v171 offset:1024
	ds_read_b128 v[200:203], v171 offset:2048
	ds_read_b128 v[204:207], v171 offset:3072
	ds_read_b128 v[208:211], v171 offset:4096
	ds_read_b128 v[212:215], v171 offset:5120
	ds_read_b128 v[216:219], v171 offset:6144
	ds_read_b128 v[220:223], v171 offset:7168
	global_load_lds_dwordx4 v[156:157], off
	v_lshl_add_u64 v[156:157], s[0:1], 0, v[140:141]
	s_add_i32 m0, s47, 0xe000
	s_nop 0
	global_load_lds_dwordx4 v[156:157], off
	s_waitcnt lgkmcnt(8)
	s_barrier
	s_waitcnt lgkmcnt(0)
	s_setprio 1
	s_waitcnt lgkmcnt(0)
	v_mfma_f32_16x16x32_bf16 v[124:127], v[146:149], v[186:189], v[124:127]
	v_mfma_f32_16x16x32_bf16 v[120:123], v[178:181], v[186:189], v[120:123]
	v_mfma_f32_16x16x32_bf16 v[108:111], v[146:149], v[200:203], v[108:111]
	v_mfma_f32_16x16x32_bf16 v[104:107], v[178:181], v[200:203], v[104:107]
	v_mfma_f32_16x16x32_bf16 v[92:95], v[146:149], v[208:211], v[92:95]
	v_mfma_f32_16x16x32_bf16 v[88:91], v[178:181], v[208:211], v[88:91]
	v_mfma_f32_16x16x32_bf16 v[76:79], v[146:149], v[216:219], v[76:79]
	v_mfma_f32_16x16x32_bf16 v[72:75], v[178:181], v[216:219], v[72:75]
	v_mfma_f32_16x16x32_bf16 v[124:127], v[150:153], v[196:199], v[124:127]
	v_mfma_f32_16x16x32_bf16 v[120:123], v[182:185], v[196:199], v[120:123]
	v_mfma_f32_16x16x32_bf16 v[108:111], v[150:153], v[204:207], v[108:111]
	v_mfma_f32_16x16x32_bf16 v[104:107], v[182:185], v[204:207], v[104:107]
	v_mfma_f32_16x16x32_bf16 v[92:95], v[150:153], v[212:215], v[92:95]
	v_mfma_f32_16x16x32_bf16 v[88:91], v[182:185], v[212:215], v[88:91]
	v_mfma_f32_16x16x32_bf16 v[76:79], v[150:153], v[220:223], v[76:79]
	v_mfma_f32_16x16x32_bf16 v[72:75], v[182:185], v[220:223], v[72:75]
	s_setprio 0
	s_barrier
	s_add_i32 s28, s56, s11
	v_lshl_add_u64 v[156:157], s[42:43], 0, v[132:133]
	s_mov_b32 m0, s28
	ds_read_b128 v[224:227], v175
	ds_read_b128 v[228:231], v175 offset:1024
	ds_read_b128 v[232:235], v175 offset:2048
	ds_read_b128 v[236:239], v175 offset:3072
	global_load_lds_dwordx4 v[156:157], off
	v_lshl_add_u64 v[160:161], s[42:43], 0, v[128:129]
	s_add_i32 m0, s28, 0x2000
	s_nop 0
	global_load_lds_dwordx4 v[160:161], off
	s_barrier
	s_waitcnt lgkmcnt(0)
	s_setprio 1
	s_waitcnt lgkmcnt(0)
	v_mfma_f32_16x16x32_bf16 v[116:119], v[224:227], v[186:189], v[116:119]
	v_mfma_f32_16x16x32_bf16 v[112:115], v[232:235], v[186:189], v[112:115]
	v_mfma_f32_16x16x32_bf16 v[100:103], v[224:227], v[200:203], v[100:103]
	v_mfma_f32_16x16x32_bf16 v[96:99], v[232:235], v[200:203], v[96:99]
	v_mfma_f32_16x16x32_bf16 v[84:87], v[224:227], v[208:211], v[84:87]
	v_mfma_f32_16x16x32_bf16 v[80:83], v[232:235], v[208:211], v[80:83]
	v_mfma_f32_16x16x32_bf16 v[68:71], v[224:227], v[216:219], v[68:71]
	v_mfma_f32_16x16x32_bf16 v[64:67], v[232:235], v[216:219], v[64:67]
	v_mfma_f32_16x16x32_bf16 v[116:119], v[228:231], v[196:199], v[116:119]
	v_mfma_f32_16x16x32_bf16 v[112:115], v[236:239], v[196:199], v[112:115]
	v_mfma_f32_16x16x32_bf16 v[100:103], v[228:231], v[204:207], v[100:103]
	v_mfma_f32_16x16x32_bf16 v[96:99], v[236:239], v[204:207], v[96:99]
	v_mfma_f32_16x16x32_bf16 v[84:87], v[228:231], v[212:215], v[84:87]
	v_mfma_f32_16x16x32_bf16 v[80:83], v[236:239], v[212:215], v[80:83]
	v_mfma_f32_16x16x32_bf16 v[68:71], v[228:231], v[220:223], v[68:71]
	v_mfma_f32_16x16x32_bf16 v[64:67], v[236:239], v[220:223], v[64:67]
	s_setprio 0
	s_mov_b32 m0, s47
	v_lshl_add_u64 v[164:165], s[44:45], 0, v[134:135]
	s_barrier
	ds_read_b128 v[186:189], v171 offset:16384
	ds_read_b128 v[196:199], v171 offset:17408
	ds_read_b128 v[200:203], v171 offset:18432
	ds_read_b128 v[204:207], v171 offset:19456
	ds_read_b128 v[208:211], v171 offset:20480
	ds_read_b128 v[212:215], v171 offset:21504
	ds_read_b128 v[216:219], v171 offset:22528
	ds_read_b128 v[220:223], v171 offset:23552
	global_load_lds_dwordx4 v[164:165], off
	v_lshl_add_u64 v[168:169], s[44:45], 0, v[130:131]
	s_mov_b32 m0, s48
	s_nop 0
	global_load_lds_dwordx4 v[168:169], off
	s_barrier
	s_waitcnt lgkmcnt(0)
	s_setprio 1
	s_waitcnt lgkmcnt(0)
	v_mfma_f32_16x16x32_bf16 v[60:63], v[146:149], v[186:189], v[60:63]
	v_mfma_f32_16x16x32_bf16 v[56:59], v[178:181], v[186:189], v[56:59]
	v_mfma_f32_16x16x32_bf16 v[44:47], v[146:149], v[200:203], v[44:47]
	v_mfma_f32_16x16x32_bf16 v[40:43], v[178:181], v[200:203], v[40:43]
	v_mfma_f32_16x16x32_bf16 v[28:31], v[146:149], v[208:211], v[28:31]
	v_mfma_f32_16x16x32_bf16 v[24:27], v[178:181], v[208:211], v[24:27]
	v_mfma_f32_16x16x32_bf16 v[12:15], v[146:149], v[216:219], v[12:15]
	v_mfma_f32_16x16x32_bf16 v[8:11], v[178:181], v[216:219], v[8:11]
	v_mfma_f32_16x16x32_bf16 v[60:63], v[150:153], v[196:199], v[60:63]
	v_mfma_f32_16x16x32_bf16 v[56:59], v[182:185], v[196:199], v[56:59]
	v_mfma_f32_16x16x32_bf16 v[44:47], v[150:153], v[204:207], v[44:47]
	v_mfma_f32_16x16x32_bf16 v[40:43], v[182:185], v[204:207], v[40:43]
	v_mfma_f32_16x16x32_bf16 v[28:31], v[150:153], v[212:215], v[28:31]
	v_mfma_f32_16x16x32_bf16 v[24:27], v[182:185], v[212:215], v[24:27]
	v_mfma_f32_16x16x32_bf16 v[12:15], v[150:153], v[220:223], v[12:15]
	v_mfma_f32_16x16x32_bf16 v[8:11], v[182:185], v[220:223], v[8:11]
	s_setprio 0
	s_barrier
	s_add_u32 s66, s42, 0x40000
	s_addc_u32 s67, s43, 0
	s_add_i32 s28, s57, s11
	v_lshl_add_u64 v[146:147], s[66:67], 0, v[132:133]
	s_mov_b32 m0, s28
	s_nop 0
	global_load_lds_dwordx4 v[146:147], off
	v_lshl_add_u64 v[146:147], s[66:67], 0, v[128:129]
	s_add_i32 m0, s28, 0x2000
	s_nop 0
	global_load_lds_dwordx4 v[146:147], off
	s_cmp_eq_u32 s98, 0
	s_cbranch_scc1 .Lk10_w4n
	s_mov_b32 s98, 0
	s_waitcnt vmcnt(24)
	s_branch .Lk10_w4j

.Lk10_w4j:
	s_barrier
	s_setprio 1
	v_mfma_f32_16x16x32_bf16 v[52:55], v[224:227], v[186:189], v[52:55]
	v_mfma_f32_16x16x32_bf16 v[48:51], v[232:235], v[186:189], v[48:51]
	v_mfma_f32_16x16x32_bf16 v[36:39], v[224:227], v[200:203], v[36:39]
	v_mfma_f32_16x16x32_bf16 v[32:35], v[232:235], v[200:203], v[32:35]
	v_mfma_f32_16x16x32_bf16 v[20:23], v[224:227], v[208:211], v[20:23]
	v_mfma_f32_16x16x32_bf16 v[16:19], v[232:235], v[208:211], v[16:19]
	v_mfma_f32_16x16x32_bf16 v[4:7], v[224:227], v[216:219], v[4:7]
	v_mfma_f32_16x16x32_bf16 v[0:3], v[232:235], v[216:219], v[0:3]
	v_mfma_f32_16x16x32_bf16 v[52:55], v[228:231], v[196:199], v[52:55]
	v_mfma_f32_16x16x32_bf16 v[48:51], v[236:239], v[196:199], v[48:51]
	v_mfma_f32_16x16x32_bf16 v[36:39], v[228:231], v[204:207], v[36:39]
	v_mfma_f32_16x16x32_bf16 v[32:35], v[236:239], v[204:207], v[32:35]
	v_mfma_f32_16x16x32_bf16 v[20:23], v[228:231], v[212:215], v[20:23]
	v_mfma_f32_16x16x32_bf16 v[16:19], v[236:239], v[212:215], v[16:19]
	v_mfma_f32_16x16x32_bf16 v[4:7], v[228:231], v[220:223], v[4:7]
	v_mfma_f32_16x16x32_bf16 v[0:3], v[236:239], v[220:223], v[0:3]
	s_setprio 0
	s_add_i32 s28, 0, 0x18000
	v_add_u32_e32 v154, s28, v159
	s_barrier
	ds_read_b128 v[146:149], v154
	ds_read_b128 v[150:153], v154 offset:1024
	ds_read_b128 v[178:181], v154 offset:2048
	ds_read_b128 v[182:185], v154 offset:3072
	s_add_u32 s44, s44, 0x40000
	s_addc_u32 s45, s45, 0
	s_mov_b32 m0, s49
	v_lshl_add_u64 v[172:173], s[44:45], 0, v[134:135]
	ds_read_b128 v[186:189], v171 offset:32768
	ds_read_b128 v[196:199], v171 offset:33792
	ds_read_b128 v[200:203], v171 offset:34816
	ds_read_b128 v[204:207], v171 offset:35840
	ds_read_b128 v[208:211], v171 offset:36864
	ds_read_b128 v[212:215], v171 offset:37888
	ds_read_b128 v[216:219], v171 offset:38912
	ds_read_b128 v[220:223], v171 offset:39936
	global_load_lds_dwordx4 v[172:173], off
	v_lshl_add_u64 v[172:173], s[44:45], 0, v[130:131]
	s_mov_b32 m0, s50
	s_nop 0
	global_load_lds_dwordx4 v[172:173], off
	s_waitcnt lgkmcnt(8)
	s_barrier
	s_waitcnt lgkmcnt(0)
	s_setprio 1
	s_waitcnt lgkmcnt(0)
	v_mfma_f32_16x16x32_bf16 v[124:127], v[146:149], v[186:189], v[124:127]
	v_mfma_f32_16x16x32_bf16 v[120:123], v[178:181], v[186:189], v[120:123]
	v_mfma_f32_16x16x32_bf16 v[108:111], v[146:149], v[200:203], v[108:111]
	v_mfma_f32_16x16x32_bf16 v[104:107], v[178:181], v[200:203], v[104:107]
	v_mfma_f32_16x16x32_bf16 v[92:95], v[146:149], v[208:211], v[92:95]
	v_mfma_f32_16x16x32_bf16 v[88:91], v[178:181], v[208:211], v[88:91]
	v_mfma_f32_16x16x32_bf16 v[76:79], v[146:149], v[216:219], v[76:79]
	v_mfma_f32_16x16x32_bf16 v[72:75], v[178:181], v[216:219], v[72:75]
	v_mfma_f32_16x16x32_bf16 v[124:127], v[150:153], v[196:199], v[124:127]
	v_mfma_f32_16x16x32_bf16 v[120:123], v[182:185], v[196:199], v[120:123]
	v_mfma_f32_16x16x32_bf16 v[108:111], v[150:153], v[204:207], v[108:111]
	v_mfma_f32_16x16x32_bf16 v[104:107], v[182:185], v[204:207], v[104:107]
	v_mfma_f32_16x16x32_bf16 v[92:95], v[150:153], v[212:215], v[92:95]
	v_mfma_f32_16x16x32_bf16 v[88:91], v[182:185], v[212:215], v[88:91]
	v_mfma_f32_16x16x32_bf16 v[76:79], v[150:153], v[220:223], v[76:79]
	v_mfma_f32_16x16x32_bf16 v[72:75], v[182:185], v[220:223], v[72:75]
	s_setprio 0
	s_barrier
	s_add_i32 s29, 0, 0x1c000
	s_add_i32 s28, s28, s11
	v_add_u32_e32 v154, s29, v159
	v_lshl_add_u64 v[156:157], v[156:157], 0, s[6:7]
	s_mov_b32 m0, s28
	ds_read_b128 v[224:227], v154
	ds_read_b128 v[228:231], v154 offset:1024
	ds_read_b128 v[232:235], v154 offset:2048
	ds_read_b128 v[236:239], v154 offset:3072
	global_load_lds_dwordx4 v[156:157], off
	v_lshl_add_u64 v[156:157], v[160:161], 0, s[6:7]
	s_add_i32 m0, s28, 0x2000
	s_nop 0
	global_load_lds_dwordx4 v[156:157], off
	s_barrier
	s_waitcnt lgkmcnt(0)
	s_setprio 1
	s_waitcnt lgkmcnt(0)
	v_mfma_f32_16x16x32_bf16 v[116:119], v[224:227], v[186:189], v[116:119]
	v_mfma_f32_16x16x32_bf16 v[112:115], v[232:235], v[186:189], v[112:115]
	v_mfma_f32_16x16x32_bf16 v[100:103], v[224:227], v[200:203], v[100:103]
	v_mfma_f32_16x16x32_bf16 v[96:99], v[232:235], v[200:203], v[96:99]
	v_mfma_f32_16x16x32_bf16 v[84:87], v[224:227], v[208:211], v[84:87]
	v_mfma_f32_16x16x32_bf16 v[80:83], v[232:235], v[208:211], v[80:83]
	v_mfma_f32_16x16x32_bf16 v[68:71], v[224:227], v[216:219], v[68:71]
	v_mfma_f32_16x16x32_bf16 v[64:67], v[232:235], v[216:219], v[64:67]
	v_mfma_f32_16x16x32_bf16 v[116:119], v[228:231], v[196:199], v[116:119]
	v_mfma_f32_16x16x32_bf16 v[112:115], v[236:239], v[196:199], v[112:115]
	v_mfma_f32_16x16x32_bf16 v[100:103], v[228:231], v[204:207], v[100:103]
	v_mfma_f32_16x16x32_bf16 v[96:99], v[236:239], v[204:207], v[96:99]
	v_mfma_f32_16x16x32_bf16 v[84:87], v[228:231], v[212:215], v[84:87]
	v_mfma_f32_16x16x32_bf16 v[80:83], v[236:239], v[212:215], v[80:83]
	v_mfma_f32_16x16x32_bf16 v[68:71], v[228:231], v[220:223], v[68:71]
	v_mfma_f32_16x16x32_bf16 v[64:67], v[236:239], v[220:223], v[64:67]
	s_setprio 0
	s_mov_b32 m0, s53
	v_lshl_add_u64 v[156:157], v[164:165], 0, s[6:7]
	s_waitcnt vmcnt(10)
	s_barrier
	ds_read_b128 v[186:189], v171 offset:49152
	ds_read_b128 v[196:199], v171 offset:50176
	ds_read_b128 v[200:203], v171 offset:51200
	ds_read_b128 v[204:207], v171 offset:52224
	ds_read_b128 v[208:211], v171 offset:53248
	ds_read_b128 v[212:215], v171 offset:54272
	ds_read_b128 v[216:219], v171 offset:55296
	ds_read_b128 v[220:223], v171 offset:56320
	global_load_lds_dwordx4 v[156:157], off
	v_lshl_add_u64 v[156:157], v[168:169], 0, s[6:7]
	s_mov_b32 m0, s54
	s_nop 0
	global_load_lds_dwordx4 v[156:157], off
	s_barrier
	s_waitcnt lgkmcnt(0)
	s_setprio 1
	s_waitcnt lgkmcnt(0)
	v_mfma_f32_16x16x32_bf16 v[60:63], v[146:149], v[186:189], v[60:63]
	v_mfma_f32_16x16x32_bf16 v[56:59], v[178:181], v[186:189], v[56:59]
	v_mfma_f32_16x16x32_bf16 v[44:47], v[146:149], v[200:203], v[44:47]
	v_mfma_f32_16x16x32_bf16 v[40:43], v[178:181], v[200:203], v[40:43]
	v_mfma_f32_16x16x32_bf16 v[28:31], v[146:149], v[208:211], v[28:31]
	v_mfma_f32_16x16x32_bf16 v[24:27], v[178:181], v[208:211], v[24:27]
	v_mfma_f32_16x16x32_bf16 v[12:15], v[146:149], v[216:219], v[12:15]
	v_mfma_f32_16x16x32_bf16 v[8:11], v[178:181], v[216:219], v[8:11]
	v_mfma_f32_16x16x32_bf16 v[60:63], v[150:153], v[196:199], v[60:63]
	v_mfma_f32_16x16x32_bf16 v[56:59], v[182:185], v[196:199], v[56:59]
	v_mfma_f32_16x16x32_bf16 v[44:47], v[150:153], v[204:207], v[44:47]
	v_mfma_f32_16x16x32_bf16 v[40:43], v[182:185], v[204:207], v[40:43]
	v_mfma_f32_16x16x32_bf16 v[28:31], v[150:153], v[212:215], v[28:31]
	v_mfma_f32_16x16x32_bf16 v[24:27], v[182:185], v[212:215], v[24:27]
	v_mfma_f32_16x16x32_bf16 v[12:15], v[150:153], v[220:223], v[12:15]
	v_mfma_f32_16x16x32_bf16 v[8:11], v[182:185], v[220:223], v[8:11]
	s_setprio 0
	s_barrier
	s_add_u32 s42, s42, 0x40080
	s_addc_u32 s43, s43, 0
	s_add_i32 s28, s29, s11
	v_lshl_add_u64 v[146:147], s[42:43], 0, v[132:133]
	s_mov_b32 m0, s28
	s_nop 0
	global_load_lds_dwordx4 v[146:147], off
	v_lshl_add_u64 v[146:147], s[42:43], 0, v[128:129]
	s_add_i32 m0, s28, 0x2000
	s_nop 0
	global_load_lds_dwordx4 v[146:147], off
	s_waitcnt vmcnt(6)
	s_barrier
	s_setprio 1
	v_mfma_f32_16x16x32_bf16 v[52:55], v[224:227], v[186:189], v[52:55]
	v_mfma_f32_16x16x32_bf16 v[48:51], v[232:235], v[186:189], v[48:51]
	v_mfma_f32_16x16x32_bf16 v[36:39], v[224:227], v[200:203], v[36:39]
	v_mfma_f32_16x16x32_bf16 v[32:35], v[232:235], v[200:203], v[32:35]
	v_mfma_f32_16x16x32_bf16 v[20:23], v[224:227], v[208:211], v[20:23]
	v_mfma_f32_16x16x32_bf16 v[16:19], v[232:235], v[208:211], v[16:19]
	v_mfma_f32_16x16x32_bf16 v[4:7], v[224:227], v[216:219], v[4:7]
	v_mfma_f32_16x16x32_bf16 v[0:3], v[232:235], v[216:219], v[0:3]
	v_mfma_f32_16x16x32_bf16 v[52:55], v[228:231], v[196:199], v[52:55]
	v_mfma_f32_16x16x32_bf16 v[48:51], v[236:239], v[196:199], v[48:51]
	v_mfma_f32_16x16x32_bf16 v[36:39], v[228:231], v[204:207], v[36:39]
	v_mfma_f32_16x16x32_bf16 v[32:35], v[236:239], v[204:207], v[32:35]
	v_mfma_f32_16x16x32_bf16 v[20:23], v[228:231], v[212:215], v[20:23]
	v_mfma_f32_16x16x32_bf16 v[16:19], v[236:239], v[212:215], v[16:19]
	v_mfma_f32_16x16x32_bf16 v[4:7], v[228:231], v[220:223], v[4:7]
	v_mfma_f32_16x16x32_bf16 v[0:3], v[236:239], v[220:223], v[0:3]
	s_setprio 0
	s_add_i32 s64, s64, 2
	s_add_u32 s0, s0, 0x100
	s_addc_u32 s1, s1, 0
	s_add_u32 s62, s62, 0x100
	s_addc_u32 s63, s63, 0
	s_cmp_gt_u32 s64, 13
	s_barrier
	s_cbranch_scc0 .LBB0_1093
	v_lshl_add_u32 v168, s4, 8, v155
	v_or_b32_e32 v164, 16, v168
	v_or_b32_e32 v160, 32, v168
	v_or_b32_e32 v156, 48, v168
	v_add_u32_e32 v152, 0x80, v168
	v_add_u32_e32 v150, 0x90, v168
	v_add_u32_e32 v148, 0xa0, v168
	v_add_u32_e32 v146, 0xb0, v168
	v_lshl_or_b32 v172, s5, 7, v163
	v_mov_b32_e32 v178, v240
	v_mov_b32_e32 v179, v240
	v_mov_b32_e32 v154, v241
	s_and_b32 s0, s36, 0x7f
	v_lshl_add_u32 v228, s0, 8, v155
	v_mov_b32_e32 v229, 0
	v_lshlrev_b32_e32 v228, 6, v228
	v_lshl_add_u64 v[230:231], v[136:137], 0, v[228:229]
	v_mov_b32_e32 v228, 0x2000
	v_lshl_add_u64 v[232:233], v[230:231], 0, v[228:229]
	global_load_dwordx4 v[216:219], v[230:231], off
	global_load_dwordx4 v[220:223], v[230:231], off offset:1024
	global_load_dwordx4 v[224:227], v[230:231], off offset:2048
	global_load_dwordx4 v[196:199], v[230:231], off offset:3072
	global_load_dwordx4 v[200:203], v[232:233], off
	global_load_dwordx4 v[204:207], v[232:233], off offset:1024
	global_load_dwordx4 v[208:211], v[232:233], off offset:2048
	global_load_dwordx4 v[212:215], v[232:233], off offset:3072
	v_pk_mul_f32 v[124:125], v[124:125], v[178:179] op_sel_hi:[1,0]
	v_pk_mul_f32 v[126:127], v[126:127], v[178:179] op_sel_hi:[1,0]
	v_mul_f32_e32 v147, 0xbfb8aa3b, v124
	v_exp_f32_e32 v147, v147
	v_mul_f32_e32 v149, 0xbfb8aa3b, v125
	v_exp_f32_e32 v149, v149
	v_mul_f32_e32 v151, 0xbfb8aa3b, v127
	v_add_f32_e32 v147, 1.0, v147
	v_rcp_f32_e32 v180, v147
	v_add_f32_e32 v147, 1.0, v149
	v_mul_f32_e32 v149, 0xbfb8aa3b, v126
	v_exp_f32_e32 v149, v149
	v_exp_f32_e32 v151, v151
	v_rcp_f32_e32 v181, v147
	v_pk_mul_f32 v[116:117], v[116:117], v[178:179] op_sel_hi:[1,0]
	v_add_f32_e32 v147, 1.0, v149
	v_rcp_f32_e32 v182, v147
	v_add_f32_e32 v147, 1.0, v151
	v_rcp_f32_e32 v183, v147
	v_pk_mul_f32 v[124:125], v[124:125], v[180:181]
	v_pk_mul_f32 v[120:121], v[120:121], v[178:179] op_sel_hi:[1,0]
	v_pk_mul_f32 v[116:117], v[116:117], v[124:125]
	v_pk_mul_f32 v[124:125], v[126:127], v[182:183]
	v_mul_f32_e32 v126, 0xbfb8aa3b, v120
	v_exp_f32_e32 v126, v126
	v_pk_mul_f32 v[118:119], v[118:119], v[178:179] op_sel_hi:[1,0]
	v_pk_mul_f32 v[122:123], v[122:123], v[178:179] op_sel_hi:[1,0]
	v_pk_mul_f32 v[118:119], v[118:119], v[124:125]
	v_mul_f32_e32 v124, 0xbfb8aa3b, v121
	v_exp_f32_e32 v125, v124
	v_add_f32_e32 v124, 1.0, v126
	v_mul_f32_e32 v126, 0xbfb8aa3b, v122
	v_mul_f32_e32 v127, 0xbfb8aa3b, v123
	v_exp_f32_e32 v126, v126
	v_exp_f32_e32 v127, v127
	v_add_f32_e32 v125, 1.0, v125
	v_rcp_f32_e32 v124, v124
	v_rcp_f32_e32 v125, v125
	v_add_f32_e32 v126, 1.0, v126
	v_add_f32_e32 v127, 1.0, v127
	v_rcp_f32_e32 v126, v126
	v_rcp_f32_e32 v127, v127
	v_pk_mul_f32 v[112:113], v[112:113], v[178:179] op_sel_hi:[1,0]
	v_pk_mul_f32 v[120:121], v[120:121], v[124:125]
	v_pk_mul_f32 v[114:115], v[114:115], v[178:179] op_sel_hi:[1,0]
	v_pk_mul_f32 v[112:113], v[112:113], v[120:121]
	v_pk_mul_f32 v[120:121], v[122:123], v[126:127]
	v_ashrrev_i32_e32 v173, 31, v172
	v_pk_mul_f32 v[114:115], v[114:115], v[120:121]
	v_cvt_pk_bf16_f32 v116, v116, v117
	v_cvt_pk_bf16_f32 v117, v118, v119
	v_cvt_pk_bf16_f32 v118, v112, v113
	v_mov_b64_e32 v[112:113], s[20:21]
	v_cvt_pk_bf16_f32 v119, v114, v115
	v_mad_i64_i32 v[120:121], s[0:1], v168, s59, v[112:113]
	v_lshlrev_b64 v[114:115], 1, v[172:173]
	v_lshl_add_u64 v[120:121], v[120:121], 0, v[114:115]
	v_pk_mul_f32 v[108:109], v[108:109], v[176:177] op_sel_hi:[1,0]
	global_store_dwordx4 v[120:121], v[116:119], off
	v_mul_f32_e32 v122, 0xbfb8aa3b, v108
	v_pk_mul_f32 v[110:111], v[110:111], v[176:177] op_sel_hi:[1,0]
	v_mul_f32_e32 v116, 0xbfb8aa3b, v109
	v_exp_f32_e32 v122, v122
	v_exp_f32_e32 v117, v116
	v_mul_f32_e32 v118, 0xbfb8aa3b, v110
	v_mul_f32_e32 v119, 0xbfb8aa3b, v111
	v_exp_f32_e32 v118, v118
	v_exp_f32_e32 v119, v119
	v_add_f32_e32 v116, 1.0, v122
	v_add_f32_e32 v117, 1.0, v117
	v_rcp_f32_e32 v116, v116
	v_rcp_f32_e32 v117, v117
	v_add_f32_e32 v118, 1.0, v118
	v_add_f32_e32 v119, 1.0, v119
	v_rcp_f32_e32 v118, v118
	v_rcp_f32_e32 v119, v119
	v_pk_mul_f32 v[100:101], v[100:101], v[176:177] op_sel_hi:[1,0]
	v_pk_mul_f32 v[108:109], v[108:109], v[116:117]
	v_pk_mul_f32 v[104:105], v[104:105], v[176:177] op_sel_hi:[1,0]
	v_pk_mul_f32 v[100:101], v[100:101], v[108:109]
	v_pk_mul_f32 v[108:109], v[110:111], v[118:119]
	v_mul_f32_e32 v110, 0xbfb8aa3b, v104
	v_exp_f32_e32 v110, v110
	v_pk_mul_f32 v[102:103], v[102:103], v[176:177] op_sel_hi:[1,0]
	v_pk_mul_f32 v[106:107], v[106:107], v[176:177] op_sel_hi:[1,0]
	v_pk_mul_f32 v[102:103], v[102:103], v[108:109]
	v_mul_f32_e32 v108, 0xbfb8aa3b, v105
	v_exp_f32_e32 v109, v108
	v_add_f32_e32 v108, 1.0, v110
	v_mul_f32_e32 v110, 0xbfb8aa3b, v106
	v_mul_f32_e32 v111, 0xbfb8aa3b, v107
	v_exp_f32_e32 v110, v110
	v_exp_f32_e32 v111, v111
	v_add_f32_e32 v109, 1.0, v109
	v_rcp_f32_e32 v108, v108
	v_rcp_f32_e32 v109, v109
	v_add_f32_e32 v110, 1.0, v110
	v_add_f32_e32 v111, 1.0, v111
	v_rcp_f32_e32 v110, v110
	v_rcp_f32_e32 v111, v111
	v_pk_mul_f32 v[96:97], v[96:97], v[176:177] op_sel_hi:[1,0]
	v_pk_mul_f32 v[104:105], v[104:105], v[108:109]
	v_pk_mul_f32 v[92:93], v[92:93], v[174:175] op_sel_hi:[1,0]
	v_pk_mul_f32 v[104:105], v[96:97], v[104:105]
	v_pk_mul_f32 v[96:97], v[98:99], v[176:177] op_sel_hi:[1,0]
	v_pk_mul_f32 v[98:99], v[106:107], v[110:111]
	v_pk_mul_f32 v[94:95], v[94:95], v[174:175] op_sel_hi:[1,0]
	v_pk_mul_f32 v[106:107], v[96:97], v[98:99]
	v_cvt_pk_bf16_f32 v96, v100, v101
	v_mad_i64_i32 v[100:101], s[0:1], v164, s59, v[112:113]
	v_cvt_pk_bf16_f32 v97, v102, v103
	v_cvt_pk_bf16_f32 v98, v104, v105
	v_cvt_pk_bf16_f32 v99, v106, v107
	v_lshl_add_u64 v[100:101], v[100:101], 0, v[114:115]
	v_mul_f32_e32 v102, 0xbfb8aa3b, v92
	global_store_dwordx4 v[100:101], v[96:99], off
	v_exp_f32_e32 v102, v102
	v_pk_mul_f32 v[84:85], v[84:85], v[174:175] op_sel_hi:[1,0]
	v_mul_f32_e32 v96, 0xbfb8aa3b, v93
	v_exp_f32_e32 v97, v96
	v_mul_f32_e32 v98, 0xbfb8aa3b, v94
	v_mul_f32_e32 v99, 0xbfb8aa3b, v95
	v_exp_f32_e32 v98, v98
	v_exp_f32_e32 v99, v99
	v_add_f32_e32 v96, 1.0, v102
	v_add_f32_e32 v97, 1.0, v97
	v_rcp_f32_e32 v96, v96
	v_rcp_f32_e32 v97, v97
	v_add_f32_e32 v98, 1.0, v98
	v_add_f32_e32 v99, 1.0, v99
	v_rcp_f32_e32 v98, v98
	v_rcp_f32_e32 v99, v99
	v_pk_mul_f32 v[92:93], v[92:93], v[96:97]
	v_pk_mul_f32 v[88:89], v[88:89], v[174:175] op_sel_hi:[1,0]
	v_pk_mul_f32 v[84:85], v[84:85], v[92:93]
	v_pk_mul_f32 v[92:93], v[94:95], v[98:99]
	v_mul_f32_e32 v94, 0xbfb8aa3b, v88
	v_exp_f32_e32 v94, v94
	v_pk_mul_f32 v[86:87], v[86:87], v[174:175] op_sel_hi:[1,0]
	v_pk_mul_f32 v[90:91], v[90:91], v[174:175] op_sel_hi:[1,0]
	v_pk_mul_f32 v[86:87], v[86:87], v[92:93]
	v_mul_f32_e32 v92, 0xbfb8aa3b, v89
	v_exp_f32_e32 v93, v92
	v_add_f32_e32 v92, 1.0, v94
	v_mul_f32_e32 v94, 0xbfb8aa3b, v90
	v_mul_f32_e32 v95, 0xbfb8aa3b, v91
	v_exp_f32_e32 v94, v94
	v_exp_f32_e32 v95, v95
	v_add_f32_e32 v93, 1.0, v93
	v_rcp_f32_e32 v92, v92
	v_rcp_f32_e32 v93, v93
	v_add_f32_e32 v94, 1.0, v94
	v_add_f32_e32 v95, 1.0, v95
	v_rcp_f32_e32 v94, v94
	v_rcp_f32_e32 v95, v95
	v_pk_mul_f32 v[80:81], v[80:81], v[174:175] op_sel_hi:[1,0]
	v_pk_mul_f32 v[88:89], v[88:89], v[92:93]
	v_pk_mul_f32 v[76:77], v[76:77], v[170:171] op_sel_hi:[1,0]
	v_pk_mul_f32 v[88:89], v[80:81], v[88:89]
	v_pk_mul_f32 v[80:81], v[82:83], v[174:175] op_sel_hi:[1,0]
	v_pk_mul_f32 v[82:83], v[90:91], v[94:95]
	v_pk_mul_f32 v[78:79], v[78:79], v[170:171] op_sel_hi:[1,0]
	v_pk_mul_f32 v[90:91], v[80:81], v[82:83]
	v_cvt_pk_bf16_f32 v80, v84, v85
	v_mad_i64_i32 v[84:85], s[0:1], v160, s59, v[112:113]
	v_cvt_pk_bf16_f32 v81, v86, v87
	v_cvt_pk_bf16_f32 v82, v88, v89
	v_cvt_pk_bf16_f32 v83, v90, v91
	v_lshl_add_u64 v[84:85], v[84:85], 0, v[114:115]
	v_mul_f32_e32 v86, 0xbfb8aa3b, v76
	global_store_dwordx4 v[84:85], v[80:83], off
	v_exp_f32_e32 v86, v86
	v_pk_mul_f32 v[68:69], v[68:69], v[170:171] op_sel_hi:[1,0]
	v_mul_f32_e32 v80, 0xbfb8aa3b, v77
	v_exp_f32_e32 v81, v80
	v_mul_f32_e32 v82, 0xbfb8aa3b, v78
	v_mul_f32_e32 v83, 0xbfb8aa3b, v79
	v_exp_f32_e32 v82, v82
	v_exp_f32_e32 v83, v83
	v_add_f32_e32 v80, 1.0, v86
	v_add_f32_e32 v81, 1.0, v81
	v_rcp_f32_e32 v80, v80
	v_rcp_f32_e32 v81, v81
	v_add_f32_e32 v82, 1.0, v82
	v_add_f32_e32 v83, 1.0, v83
	v_rcp_f32_e32 v82, v82
	v_rcp_f32_e32 v83, v83
	v_pk_mul_f32 v[76:77], v[76:77], v[80:81]
	v_pk_mul_f32 v[72:73], v[72:73], v[170:171] op_sel_hi:[1,0]
	v_pk_mul_f32 v[68:69], v[68:69], v[76:77]
	v_pk_mul_f32 v[76:77], v[78:79], v[82:83]
	v_mul_f32_e32 v78, 0xbfb8aa3b, v72
	v_exp_f32_e32 v78, v78
	v_pk_mul_f32 v[70:71], v[70:71], v[170:171] op_sel_hi:[1,0]
	v_pk_mul_f32 v[74:75], v[74:75], v[170:171] op_sel_hi:[1,0]
	v_pk_mul_f32 v[70:71], v[70:71], v[76:77]
	v_mul_f32_e32 v76, 0xbfb8aa3b, v73
	v_exp_f32_e32 v77, v76
	v_add_f32_e32 v76, 1.0, v78
	v_mul_f32_e32 v78, 0xbfb8aa3b, v74
	v_mul_f32_e32 v79, 0xbfb8aa3b, v75
	v_exp_f32_e32 v78, v78
	v_exp_f32_e32 v79, v79
	v_add_f32_e32 v77, 1.0, v77
	v_rcp_f32_e32 v76, v76
	v_rcp_f32_e32 v77, v77
	v_add_f32_e32 v78, 1.0, v78
	v_add_f32_e32 v79, 1.0, v79
	v_rcp_f32_e32 v78, v78
	v_rcp_f32_e32 v79, v79
	v_pk_mul_f32 v[64:65], v[64:65], v[170:171] op_sel_hi:[1,0]
	v_pk_mul_f32 v[72:73], v[72:73], v[76:77]
	v_pk_mul_f32 v[60:61], v[60:61], v[166:167] op_sel_hi:[1,0]
	v_pk_mul_f32 v[72:73], v[64:65], v[72:73]
	v_pk_mul_f32 v[64:65], v[66:67], v[170:171] op_sel_hi:[1,0]
	v_pk_mul_f32 v[66:67], v[74:75], v[78:79]
	v_pk_mul_f32 v[62:63], v[62:63], v[166:167] op_sel_hi:[1,0]
	v_pk_mul_f32 v[74:75], v[64:65], v[66:67]
	v_cvt_pk_bf16_f32 v64, v68, v69
	v_mad_i64_i32 v[68:69], s[0:1], v156, s59, v[112:113]
	v_cvt_pk_bf16_f32 v65, v70, v71
	v_cvt_pk_bf16_f32 v66, v72, v73
	v_cvt_pk_bf16_f32 v67, v74, v75
	v_lshl_add_u64 v[68:69], v[68:69], 0, v[114:115]
	v_mul_f32_e32 v70, 0xbfb8aa3b, v60
	global_store_dwordx4 v[68:69], v[64:67], off
	v_exp_f32_e32 v70, v70
	v_pk_mul_f32 v[52:53], v[52:53], v[166:167] op_sel_hi:[1,0]
	v_mul_f32_e32 v64, 0xbfb8aa3b, v61
	v_exp_f32_e32 v65, v64
	v_mul_f32_e32 v66, 0xbfb8aa3b, v62
	v_mul_f32_e32 v67, 0xbfb8aa3b, v63
	v_exp_f32_e32 v66, v66
	v_exp_f32_e32 v67, v67
	v_add_f32_e32 v64, 1.0, v70
	v_add_f32_e32 v65, 1.0, v65
	v_rcp_f32_e32 v64, v64
	v_rcp_f32_e32 v65, v65
	v_add_f32_e32 v66, 1.0, v66
	v_add_f32_e32 v67, 1.0, v67
	v_rcp_f32_e32 v66, v66
	v_rcp_f32_e32 v67, v67
	v_pk_mul_f32 v[60:61], v[60:61], v[64:65]
	v_pk_mul_f32 v[56:57], v[56:57], v[166:167] op_sel_hi:[1,0]
	v_pk_mul_f32 v[52:53], v[52:53], v[60:61]
	v_pk_mul_f32 v[60:61], v[62:63], v[66:67]
	v_mul_f32_e32 v62, 0xbfb8aa3b, v56
	v_exp_f32_e32 v62, v62
	v_pk_mul_f32 v[54:55], v[54:55], v[166:167] op_sel_hi:[1,0]
	v_pk_mul_f32 v[58:59], v[58:59], v[166:167] op_sel_hi:[1,0]
	v_pk_mul_f32 v[54:55], v[54:55], v[60:61]
	v_mul_f32_e32 v60, 0xbfb8aa3b, v57
	v_exp_f32_e32 v61, v60
	v_add_f32_e32 v60, 1.0, v62
	v_mul_f32_e32 v62, 0xbfb8aa3b, v58
	v_mul_f32_e32 v63, 0xbfb8aa3b, v59
	v_exp_f32_e32 v62, v62
	v_exp_f32_e32 v63, v63
	v_add_f32_e32 v61, 1.0, v61
	v_rcp_f32_e32 v60, v60
	v_rcp_f32_e32 v61, v61
	v_add_f32_e32 v62, 1.0, v62
	v_add_f32_e32 v63, 1.0, v63
	v_rcp_f32_e32 v62, v62
	v_rcp_f32_e32 v63, v63
	v_pk_mul_f32 v[48:49], v[48:49], v[166:167] op_sel_hi:[1,0]
	v_pk_mul_f32 v[56:57], v[56:57], v[60:61]
	v_pk_mul_f32 v[44:45], v[44:45], v[162:163] op_sel_hi:[1,0]
	v_pk_mul_f32 v[56:57], v[48:49], v[56:57]
	v_pk_mul_f32 v[48:49], v[50:51], v[166:167] op_sel_hi:[1,0]
	v_pk_mul_f32 v[50:51], v[58:59], v[62:63]
	v_pk_mul_f32 v[46:47], v[46:47], v[162:163] op_sel_hi:[1,0]
	v_pk_mul_f32 v[58:59], v[48:49], v[50:51]
	v_cvt_pk_bf16_f32 v48, v52, v53
	v_mad_i64_i32 v[52:53], s[0:1], v152, s59, v[112:113]
	v_cvt_pk_bf16_f32 v49, v54, v55
	v_cvt_pk_bf16_f32 v50, v56, v57
	v_cvt_pk_bf16_f32 v51, v58, v59
	v_lshl_add_u64 v[52:53], v[52:53], 0, v[114:115]
	v_mul_f32_e32 v54, 0xbfb8aa3b, v44
	global_store_dwordx4 v[52:53], v[48:51], off
	v_exp_f32_e32 v54, v54
	v_pk_mul_f32 v[36:37], v[36:37], v[162:163] op_sel_hi:[1,0]
	v_mul_f32_e32 v48, 0xbfb8aa3b, v45
	v_exp_f32_e32 v49, v48
	v_mul_f32_e32 v50, 0xbfb8aa3b, v46
	v_mul_f32_e32 v51, 0xbfb8aa3b, v47
	v_exp_f32_e32 v50, v50
	v_exp_f32_e32 v51, v51
	v_add_f32_e32 v48, 1.0, v54
	v_add_f32_e32 v49, 1.0, v49
	v_rcp_f32_e32 v48, v48
	v_rcp_f32_e32 v49, v49
	v_add_f32_e32 v50, 1.0, v50
	v_add_f32_e32 v51, 1.0, v51
	v_rcp_f32_e32 v50, v50
	v_rcp_f32_e32 v51, v51
	v_pk_mul_f32 v[44:45], v[44:45], v[48:49]
	v_pk_mul_f32 v[40:41], v[40:41], v[162:163] op_sel_hi:[1,0]
	v_pk_mul_f32 v[36:37], v[36:37], v[44:45]
	v_pk_mul_f32 v[44:45], v[46:47], v[50:51]
	v_mul_f32_e32 v46, 0xbfb8aa3b, v40
	v_exp_f32_e32 v46, v46
	v_pk_mul_f32 v[38:39], v[38:39], v[162:163] op_sel_hi:[1,0]
	v_pk_mul_f32 v[42:43], v[42:43], v[162:163] op_sel_hi:[1,0]
	v_pk_mul_f32 v[38:39], v[38:39], v[44:45]
	v_mul_f32_e32 v44, 0xbfb8aa3b, v41
	v_exp_f32_e32 v45, v44
	v_add_f32_e32 v44, 1.0, v46
	v_mul_f32_e32 v46, 0xbfb8aa3b, v42
	v_mul_f32_e32 v47, 0xbfb8aa3b, v43
	v_exp_f32_e32 v46, v46
	v_exp_f32_e32 v47, v47
	v_add_f32_e32 v45, 1.0, v45
	v_rcp_f32_e32 v44, v44
	v_rcp_f32_e32 v45, v45
	v_add_f32_e32 v46, 1.0, v46
	v_add_f32_e32 v47, 1.0, v47
	v_rcp_f32_e32 v46, v46
	v_rcp_f32_e32 v47, v47
	v_pk_mul_f32 v[32:33], v[32:33], v[162:163] op_sel_hi:[1,0]
	v_pk_mul_f32 v[40:41], v[40:41], v[44:45]
	v_pk_mul_f32 v[28:29], v[28:29], v[158:159] op_sel_hi:[1,0]
	v_pk_mul_f32 v[40:41], v[32:33], v[40:41]
	v_pk_mul_f32 v[32:33], v[34:35], v[162:163] op_sel_hi:[1,0]
	v_pk_mul_f32 v[34:35], v[42:43], v[46:47]
	v_pk_mul_f32 v[30:31], v[30:31], v[158:159] op_sel_hi:[1,0]
	v_pk_mul_f32 v[42:43], v[32:33], v[34:35]
	v_cvt_pk_bf16_f32 v32, v36, v37
	v_mad_i64_i32 v[36:37], s[0:1], v150, s59, v[112:113]
	v_cvt_pk_bf16_f32 v33, v38, v39
	v_cvt_pk_bf16_f32 v34, v40, v41
	v_cvt_pk_bf16_f32 v35, v42, v43
	v_lshl_add_u64 v[36:37], v[36:37], 0, v[114:115]
	v_mul_f32_e32 v38, 0xbfb8aa3b, v28
	global_store_dwordx4 v[36:37], v[32:35], off
	v_exp_f32_e32 v38, v38
	v_pk_mul_f32 v[20:21], v[20:21], v[158:159] op_sel_hi:[1,0]
	v_mul_f32_e32 v32, 0xbfb8aa3b, v29
	v_exp_f32_e32 v33, v32
	v_mul_f32_e32 v34, 0xbfb8aa3b, v30
	v_mul_f32_e32 v35, 0xbfb8aa3b, v31
	v_exp_f32_e32 v34, v34
	v_exp_f32_e32 v35, v35
	v_add_f32_e32 v32, 1.0, v38
	v_add_f32_e32 v33, 1.0, v33
	v_rcp_f32_e32 v32, v32
	v_rcp_f32_e32 v33, v33
	v_add_f32_e32 v34, 1.0, v34
	v_add_f32_e32 v35, 1.0, v35
	v_rcp_f32_e32 v34, v34
	v_rcp_f32_e32 v35, v35
	v_pk_mul_f32 v[28:29], v[28:29], v[32:33]
	v_pk_mul_f32 v[24:25], v[24:25], v[158:159] op_sel_hi:[1,0]
	v_pk_mul_f32 v[20:21], v[20:21], v[28:29]
	v_pk_mul_f32 v[28:29], v[30:31], v[34:35]
	v_mul_f32_e32 v30, 0xbfb8aa3b, v24
	v_exp_f32_e32 v30, v30
	v_pk_mul_f32 v[22:23], v[22:23], v[158:159] op_sel_hi:[1,0]
	v_pk_mul_f32 v[26:27], v[26:27], v[158:159] op_sel_hi:[1,0]
	v_pk_mul_f32 v[22:23], v[22:23], v[28:29]
	v_mul_f32_e32 v28, 0xbfb8aa3b, v25
	v_exp_f32_e32 v29, v28
	v_add_f32_e32 v28, 1.0, v30
	v_mul_f32_e32 v30, 0xbfb8aa3b, v26
	v_mul_f32_e32 v31, 0xbfb8aa3b, v27
	v_exp_f32_e32 v30, v30
	v_exp_f32_e32 v31, v31
	v_add_f32_e32 v29, 1.0, v29
	v_rcp_f32_e32 v28, v28
	v_rcp_f32_e32 v29, v29
	v_add_f32_e32 v30, 1.0, v30
	v_add_f32_e32 v31, 1.0, v31
	v_rcp_f32_e32 v30, v30
	v_rcp_f32_e32 v31, v31
	v_pk_mul_f32 v[16:17], v[16:17], v[158:159] op_sel_hi:[1,0]
	v_pk_mul_f32 v[24:25], v[24:25], v[28:29]
	v_pk_mul_f32 v[12:13], v[12:13], v[154:155] op_sel_hi:[1,0]
	v_pk_mul_f32 v[24:25], v[16:17], v[24:25]
	v_pk_mul_f32 v[16:17], v[18:19], v[158:159] op_sel_hi:[1,0]
	v_pk_mul_f32 v[18:19], v[26:27], v[30:31]
	v_pk_mul_f32 v[14:15], v[14:15], v[154:155] op_sel_hi:[1,0]
	v_pk_mul_f32 v[26:27], v[16:17], v[18:19]
	v_cvt_pk_bf16_f32 v16, v20, v21
	v_mad_i64_i32 v[20:21], s[0:1], v148, s59, v[112:113]
	v_cvt_pk_bf16_f32 v17, v22, v23
	v_cvt_pk_bf16_f32 v18, v24, v25
	v_cvt_pk_bf16_f32 v19, v26, v27
	v_lshl_add_u64 v[20:21], v[20:21], 0, v[114:115]
	v_mul_f32_e32 v22, 0xbfb8aa3b, v12
	global_store_dwordx4 v[20:21], v[16:19], off
	v_exp_f32_e32 v22, v22
	v_pk_mul_f32 v[4:5], v[4:5], v[154:155] op_sel_hi:[1,0]
	v_mul_f32_e32 v16, 0xbfb8aa3b, v13
	v_exp_f32_e32 v17, v16
	v_mul_f32_e32 v18, 0xbfb8aa3b, v14
	v_mul_f32_e32 v19, 0xbfb8aa3b, v15
	v_exp_f32_e32 v18, v18
	v_exp_f32_e32 v19, v19
	v_add_f32_e32 v16, 1.0, v22
	v_add_f32_e32 v17, 1.0, v17
	v_rcp_f32_e32 v16, v16
	v_rcp_f32_e32 v17, v17
	v_add_f32_e32 v18, 1.0, v18
	v_add_f32_e32 v19, 1.0, v19
	v_rcp_f32_e32 v18, v18
	v_rcp_f32_e32 v19, v19
	v_pk_mul_f32 v[12:13], v[12:13], v[16:17]
	v_pk_mul_f32 v[8:9], v[8:9], v[154:155] op_sel_hi:[1,0]
	v_pk_mul_f32 v[4:5], v[4:5], v[12:13]
	v_pk_mul_f32 v[12:13], v[14:15], v[18:19]
	v_mul_f32_e32 v14, 0xbfb8aa3b, v8
	v_exp_f32_e32 v14, v14
	v_pk_mul_f32 v[6:7], v[6:7], v[154:155] op_sel_hi:[1,0]
	v_pk_mul_f32 v[10:11], v[10:11], v[154:155] op_sel_hi:[1,0]
	v_pk_mul_f32 v[6:7], v[6:7], v[12:13]
	v_mul_f32_e32 v12, 0xbfb8aa3b, v9
	v_exp_f32_e32 v13, v12
	v_add_f32_e32 v12, 1.0, v14
	v_mul_f32_e32 v14, 0xbfb8aa3b, v10
	v_mul_f32_e32 v15, 0xbfb8aa3b, v11
	v_exp_f32_e32 v14, v14
	v_exp_f32_e32 v15, v15
	v_add_f32_e32 v13, 1.0, v13
	v_rcp_f32_e32 v12, v12
	v_rcp_f32_e32 v13, v13
	v_add_f32_e32 v14, 1.0, v14
	v_add_f32_e32 v15, 1.0, v15
	v_rcp_f32_e32 v14, v14
	v_rcp_f32_e32 v15, v15
	v_pk_mul_f32 v[0:1], v[0:1], v[154:155] op_sel_hi:[1,0]
	v_pk_mul_f32 v[8:9], v[8:9], v[12:13]
	s_and_b64 vcc, exec, s[2:3]
	v_pk_mul_f32 v[8:9], v[0:1], v[8:9]
	v_pk_mul_f32 v[0:1], v[2:3], v[154:155] op_sel_hi:[1,0]
	v_pk_mul_f32 v[2:3], v[10:11], v[14:15]
	s_mov_b32 s5, s12
	v_pk_mul_f32 v[10:11], v[0:1], v[2:3]
	v_cvt_pk_bf16_f32 v0, v4, v5
	v_mad_i64_i32 v[4:5], s[0:1], v146, s59, v[112:113]
	v_cvt_pk_bf16_f32 v1, v6, v7
	v_cvt_pk_bf16_f32 v2, v8, v9
	v_cvt_pk_bf16_f32 v3, v10, v11
	v_lshl_add_u64 v[4:5], v[4:5], 0, v[114:115]
	s_mov_b32 s4, s36
	s_mov_b64 s[42:43], s[40:41]
	s_mov_b64 s[44:45], s[38:39]
	global_store_dwordx4 v[4:5], v[0:3], off
	s_waitcnt vmcnt(8)
	v_mov_b32_e32 v178, v216
	v_mov_b32_e32 v179, v217
	v_mov_b32_e32 v180, v218
	v_mov_b32_e32 v181, v219
	v_mov_b32_e32 v182, v220
	v_mov_b32_e32 v183, v221
	v_mov_b32_e32 v184, v222
	v_mov_b32_e32 v185, v223
	v_mov_b32_e32 v186, v224
	v_mov_b32_e32 v187, v225
	v_mov_b32_e32 v188, v226
	v_mov_b32_e32 v189, v227
	v_and_b32_e32 v147, 64, v177
	v_add_u32_e32 v154, 64, v147
	v_xor_b32_e32 v151, 16, v177
	v_cmp_lt_i32_e32 vcc, v151, v154
	v_xor_b32_e32 v153, 32, v177
	v_mov_b64_e32 v[190:191], s[10:11]
	v_cndmask_b32_e32 v151, v177, v151, vcc
	v_lshlrev_b32_e32 v147, 2, v151
	v_cmp_lt_i32_e32 vcc, v153, v154
	v_mov_b32_e32 v216, v179
	v_mov_b32_e32 v217, v180
	v_mov_b32_e32 v179, v181
	v_mov_b32_e32 v180, v183
	v_mov_b32_e32 v181, v184
	v_mov_b32_e32 v183, v185
	v_pk_add_f32 v[178:179], v[216:217], v[178:179]
	v_pk_add_f32 v[180:181], v[180:181], v[182:183]
	v_mov_b32_e32 v183, v178
	v_mov_b32_e32 v182, v180
	v_mov_b32_e32 v178, v181
	v_mov_b32_e32 v184, v187
	v_mov_b32_e32 v185, v188
	v_mov_b32_e32 v187, v189
	v_mov_b32_e32 v188, v197
	v_mov_b32_e32 v189, v198
	v_mov_b32_e32 v197, v199
	v_pk_add_f32 v[178:179], v[182:183], v[178:179]
	v_pk_add_f32 v[184:185], v[184:185], v[186:187]
	v_pk_add_f32 v[186:187], v[188:189], v[196:197]
	ds_bpermute_b32 v183, v147, v179
	ds_bpermute_b32 v182, v147, v178
	v_mov_b32_e32 v180, v186
	v_mov_b32_e32 v181, v184
	v_mov_b32_e32 v184, v187
	v_pk_add_f32 v[180:181], v[180:181], v[184:185]
	ds_bpermute_b32 v185, v147, v181
	ds_bpermute_b32 v184, v147, v180
	v_cndmask_b32_e32 v153, v177, v153, vcc
	v_lshlrev_b32_e32 v149, 2, v153
	s_waitcnt lgkmcnt(0)
	v_pk_add_f32 v[178:179], v[178:179], v[182:183]
	ds_bpermute_b32 v183, v149, v179
	ds_bpermute_b32 v182, v149, v178
	v_pk_add_f32 v[180:181], v[180:181], v[184:185]
	ds_bpermute_b32 v185, v149, v181
	ds_bpermute_b32 v184, v149, v180
	v_mov_b32_e32 v186, v201
	s_waitcnt lgkmcnt(2)
	v_pk_add_f32 v[178:179], v[178:179], v[182:183]
	v_mov_b32_e32 v187, v202
	v_mov_b32_e32 v201, v203
	v_mov_b32_e32 v188, v205
	v_pk_fma_f32 v[178:179], v[178:179], s[8:9], v[190:191] op_sel_hi:[1,0,0]
	v_mov_b32_e32 v189, v206
	v_mov_b32_e32 v205, v207
	v_pk_add_f32 v[186:187], v[186:187], v[200:201]
	v_mul_f32_e32 v151, 0x4b800000, v179
	v_cmp_gt_f32_e32 vcc, s58, v179
	v_pk_add_f32 v[182:183], v[188:189], v[204:205]
	s_waitcnt lgkmcnt(0)
	v_pk_add_f32 v[180:181], v[180:181], v[184:185]
	v_cndmask_b32_e32 v151, v179, v151, vcc
	v_mov_b32_e32 v184, v182
	v_mov_b32_e32 v185, v186
	v_mov_b32_e32 v186, v183
	v_rsq_f32_e32 v151, v151
	v_pk_add_f32 v[182:183], v[184:185], v[186:187]
	ds_bpermute_b32 v185, v147, v183
	ds_bpermute_b32 v184, v147, v182
	v_pk_fma_f32 v[180:181], v[180:181], s[8:9], v[190:191] op_sel_hi:[1,0,0]
	v_mul_f32_e32 v153, 0x4b800000, v178
	v_cmp_gt_f32_e64 s[0:1], s58, v178
	v_mul_f32_e32 v157, 0x45800000, v151
	v_mul_f32_e32 v154, 0x4b800000, v181
	v_cndmask_b32_e64 v153, v178, v153, s[0:1]
	v_cmp_gt_f32_e64 s[4:5], s58, v181
	v_cndmask_b32_e32 v178, v151, v157, vcc
	v_mul_f32_e32 v151, 0x4b800000, v180
	v_cmp_gt_f32_e32 vcc, s58, v180
	v_cndmask_b32_e64 v154, v181, v154, s[4:5]
	v_rsq_f32_e32 v153, v153
	v_cndmask_b32_e32 v151, v180, v151, vcc
	s_waitcnt lgkmcnt(0)
	v_pk_add_f32 v[180:181], v[182:183], v[184:185]
	ds_bpermute_b32 v183, v149, v181
	ds_bpermute_b32 v182, v149, v180
	v_mov_b32_e32 v184, v213
	v_mov_b32_e32 v185, v214
	v_mov_b32_e32 v213, v215
	v_pk_add_f32 v[184:185], v[184:185], v[212:213]
	s_waitcnt lgkmcnt(0)
	v_pk_add_f32 v[180:181], v[180:181], v[182:183]
	v_mov_b32_e32 v182, v209
	v_mov_b32_e32 v183, v210
	v_mov_b32_e32 v209, v211
	v_pk_add_f32 v[182:183], v[182:183], v[208:209]
	v_mov_b32_e32 v186, v184
	v_mov_b32_e32 v187, v182
	v_mov_b32_e32 v182, v185
	v_rsq_f32_e32 v154, v154
	v_pk_add_f32 v[182:183], v[186:187], v[182:183]
	ds_bpermute_b32 v185, v147, v183
	ds_bpermute_b32 v184, v147, v182
	v_mul_f32_e32 v158, 0x45800000, v153
	v_cndmask_b32_e64 v176, v153, v158, s[0:1]
	v_mul_f32_e32 v153, 0x45800000, v154
	v_pk_fma_f32 v[180:181], v[180:181], s[8:9], v[190:191] op_sel_hi:[1,0,0]
	v_cndmask_b32_e64 v174, v154, v153, s[4:5]
	v_mul_f32_e32 v154, 0x4b800000, v181
	v_cmp_gt_f32_e64 s[0:1], s58, v181
	v_mul_f32_e32 v147, 0x4b800000, v180
	v_cmp_gt_f32_e64 s[4:5], s58, v180
	v_cndmask_b32_e64 v154, v181, v154, s[0:1]
	v_rsq_f32_e32 v151, v151
	v_cndmask_b32_e64 v147, v180, v147, s[4:5]
	s_waitcnt lgkmcnt(0)
	v_pk_add_f32 v[180:181], v[182:183], v[184:185]
	ds_bpermute_b32 v183, v149, v181
	ds_bpermute_b32 v182, v149, v180
	v_rsq_f32_e32 v154, v154
	v_mul_f32_e32 v153, 0x45800000, v151
	v_cndmask_b32_e32 v170, v151, v153, vcc
	v_rsq_f32_e32 v147, v147
	s_waitcnt lgkmcnt(0)
	v_pk_add_f32 v[180:181], v[180:181], v[182:183]
	v_mul_f32_e32 v149, 0x45800000, v154
	v_pk_fma_f32 v[180:181], v[180:181], s[8:9], v[190:191] op_sel_hi:[1,0,0]
	v_cndmask_b32_e64 v166, v154, v149, s[0:1]
	v_mul_f32_e32 v151, 0x4b800000, v181
	v_cmp_gt_f32_e32 vcc, s58, v181
	v_mul_f32_e32 v153, 0x4b800000, v180
	v_cmp_gt_f32_e64 s[0:1], s58, v180
	v_cndmask_b32_e32 v151, v181, v151, vcc
	v_rsq_f32_e32 v151, v151
	v_cndmask_b32_e64 v153, v180, v153, s[0:1]
	v_rsq_f32_e32 v153, v153
	v_mul_f32_e32 v149, 0x45800000, v147
	v_cndmask_b32_e64 v162, v147, v149, s[4:5]
	v_mul_f32_e32 v147, 0x45800000, v151
	v_cndmask_b32_e32 v158, v151, v147, vcc
	v_mul_f32_e32 v147, 0x45800000, v153
	v_cndmask_b32_e64 v154, v153, v147, s[0:1]
	v_mov_b32_e32 v240, v178
	v_mov_b32_e32 v241, v154
	s_and_b64 vcc, exec, s[2:3]
	s_mov_b32 s5, s12
	s_mov_b32 s4, s36
	s_mov_b32 s98, 1
	s_cbranch_vccz .LBB0_1090
	s_waitcnt vmcnt(0)
	s_cmpk_gt_u32 s9, 0xff
	s_cbranch_scc1 .LBB0_1097
	s_barrier
